# attention main loop hand-rewritten: software-pipelined (QK of tile kt+1 overlaps exp of tile kt), 3 LDS buffers, fragment reads prefetched with counted lgkmcnt; same math and precision
# speedup vs baseline: 1.0432x; 1.0432x over previous
.LBB0_450:
	v_mov_b32_e32 v124, v0
	s_waitcnt vmcnt(0) lgkmcnt(0)
	s_barrier
	v_readlane_b32 s56, v197, 2
	v_and_b32_e32 v125, 63, v124
	v_lshlrev_b32_e32 v126, 2, v125
	v_readlane_b32 s62, v197, 8
	v_readlane_b32 s63, v197, 9
	v_readlane_b32 s58, v197, 4
	v_readlane_b32 s59, v197, 5
	v_readlane_b32 s60, v197, 6
	v_readlane_b32 s61, v197, 7
	v_readlane_b32 s64, v197, 10
	v_readlane_b32 s65, v197, 11
	v_readlane_b32 s66, v197, 12
	v_readlane_b32 s67, v197, 13
	v_readlane_b32 s68, v197, 14
	v_readlane_b32 s69, v197, 15
	global_load_dword v4, v126, s[62:63]
	global_load_dword v5, v126, s[64:65]
	s_nop 0
	global_load_dword v6, v126, s[66:67]
	s_nop 0
	global_load_dword v7, v126, s[68:69]
	global_load_dword v8, v126, s[58:59]
	global_load_dword v9, v126, s[60:61]
	s_ashr_i32 s4, s17, 5
	s_mul_hi_i32 s12, s17, 0x2aaaaaab
	s_lshl_b32 s5, s17, 7
	s_mul_hi_i32 s13, s4, 0x2aaaaaab
	s_lshr_b32 s18, s12, 31
	s_ashr_i32 s12, s12, 5
	v_ashrrev_i32_e32 v14, 6, v124
	v_cmp_lt_i32_e32 vcc, v115, v114
	s_and_b32 s5, s5, 0xf80
	s_lshr_b32 s19, s13, 31
	s_add_i32 s20, s12, s18
	v_and_b32_e32 v128, 3, v14
	v_cndmask_b32_e32 v2, v105, v115, vcc
	v_and_b32_e32 v15, 15, v124
	s_add_i32 s12, s13, s19
	s_lshl_b32 s13, s20, 12
	v_lshl_or_b32 v16, v128, 5, s5
	v_lshlrev_b32_e32 v122, 2, v2
	v_or3_b32 v108, v16, s13, v15
	v_cmp_lt_i32_e32 vcc, v116, v114
	s_mul_i32 s12, s12, 6
	s_sub_i32 s4, s4, s12
	v_cndmask_b32_e32 v3, v105, v116, vcc
	v_lshlrev_b32_e32 v123, 2, v3
	v_cmp_lt_i32_e32 vcc, v117, v114
	v_readlane_b32 s57, v197, 3
	v_readlane_b32 s70, v197, 16
	v_cndmask_b32_e32 v10, v105, v117, vcc
	v_lshlrev_b32_e32 v10, 2, v10
	v_cmp_lt_i32_e32 vcc, v118, v114
	v_readlane_b32 s71, v197, 17
	s_lshl_b32 s4, s4, 7
	v_cndmask_b32_e32 v11, v105, v118, vcc
	v_lshlrev_b32_e32 v11, 2, v11
	v_cmp_lt_i32_e32 vcc, v119, v114
	s_ashr_i32 s5, s4, 31
	v_readlane_b32 s56, v196, 6
	v_cndmask_b32_e32 v12, v105, v119, vcc
	v_lshlrev_b32_e32 v12, 2, v12
	v_cmp_lt_i32_e32 vcc, v120, v114
	v_ashrrev_i32_e32 v127, 8, v124
	s_lshl_b64 s[12:13], s[4:5], 1
	v_cndmask_b32_e32 v13, v105, v120, vcc
	v_lshlrev_b32_e32 v13, 2, v13
	v_readlane_b32 s60, v196, 10
	v_lshlrev_b32_e32 v2, 6, v127
	v_readlane_b32 s61, v196, 11
	s_add_u32 s18, s60, s12
	v_ashrrev_i32_e32 v3, 31, v2
	s_addc_u32 s19, s61, s13
	v_and_b32_e32 v98, 48, v124
	v_lshl_add_u64 v[2:3], v[2:3], 1, s[18:19]
	s_mov_b32 s18, 0x3f828f5c
	v_lshl_add_u64 v[2:3], v[2:3], 0, v[98:99]
	v_or_b32_e32 v106, 16, v108
	v_bfe_u32 v121, v124, 4, 2
	v_ashrrev_i32_e32 v109, 31, v108
	v_ashrrev_i32_e32 v107, 31, v106
	v_lshlrev_b32_e32 v134, 13, v127
	v_mov_b32_e32 v20, v99
	v_mov_b32_e32 v21, v99
	v_mov_b32_e32 v26, v99
	v_mov_b32_e32 v27, v99
	v_mov_b32_e32 v28, v99
	v_mov_b32_e32 v29, v99
	v_mov_b32_e32 v30, v99
	v_mov_b32_e32 v31, v99
	v_mov_b32_e32 v32, v99
	v_mov_b32_e32 v33, v99
	v_mov_b32_e32 v34, v99
	v_mov_b32_e32 v35, v99
	v_mov_b32_e32 v36, v99
	v_mov_b32_e32 v37, v99
	v_mov_b32_e32 v38, v99
	v_mov_b32_e32 v39, v99
	s_waitcnt vmcnt(4)
	v_mul_f32_e32 v16, v4, v5
	ds_bpermute_b32 v16, v122, v16
	s_waitcnt vmcnt(2)
	v_mul_f32_e32 v17, v6, v7
	s_waitcnt vmcnt(1)
	v_and_b32_e32 v18, 0x7fffffff, v8
	s_waitcnt vmcnt(0)
	v_and_b32_e32 v19, 0x7fffffff, v9
	ds_bpermute_b32 v18, v122, v18
	ds_bpermute_b32 v19, v122, v19
	ds_bpermute_b32 v17, v122, v17
	v_max_f32_e64 v8, |v8|, |v8|
	v_max_f32_e64 v9, |v9|, |v9|
	s_waitcnt lgkmcnt(3)
	v_fmac_f32_e32 v16, v4, v5
	s_waitcnt lgkmcnt(2)
	v_max_f32_e32 v4, v18, v18
	s_waitcnt lgkmcnt(1)
	v_max_f32_e32 v5, v19, v19
	v_max_f32_e32 v4, v8, v4
	v_max_f32_e32 v5, v9, v5
	ds_bpermute_b32 v8, v123, v4
	ds_bpermute_b32 v9, v123, v5
	s_waitcnt lgkmcnt(2)
	v_fmac_f32_e32 v17, v6, v7
	ds_bpermute_b32 v6, v123, v16
	ds_bpermute_b32 v7, v123, v17
	s_waitcnt lgkmcnt(3)
	v_max_f32_e32 v8, v8, v8
	s_waitcnt lgkmcnt(2)
	v_max_f32_e32 v9, v9, v9
	v_max_f32_e32 v4, v4, v8
	v_max_f32_e32 v5, v5, v9
	s_waitcnt lgkmcnt(1)
	v_add_f32_e32 v6, v16, v6
	s_waitcnt lgkmcnt(0)
	v_add_f32_e32 v7, v17, v7
	ds_bpermute_b32 v8, v10, v4
	ds_bpermute_b32 v9, v10, v5
	ds_bpermute_b32 v16, v10, v6
	ds_bpermute_b32 v17, v10, v7
	v_mov_b32_e32 v18, v99
	s_waitcnt lgkmcnt(3)
	v_max_f32_e32 v8, v8, v8
	s_waitcnt lgkmcnt(2)
	v_max_f32_e32 v9, v9, v9
	s_waitcnt lgkmcnt(1)
	v_add_f32_e32 v6, v6, v16
	s_waitcnt lgkmcnt(0)
	v_add_f32_e32 v7, v7, v17
	v_max_f32_e32 v4, v4, v8
	v_max_f32_e32 v5, v5, v9
	ds_bpermute_b32 v10, v11, v6
	ds_bpermute_b32 v16, v11, v7
	ds_bpermute_b32 v8, v11, v4
	ds_bpermute_b32 v9, v11, v5
	v_mov_b32_e32 v19, v99
	s_waitcnt lgkmcnt(3)
	v_add_f32_e32 v6, v6, v10
	s_waitcnt lgkmcnt(2)
	v_add_f32_e32 v7, v7, v16
	s_waitcnt lgkmcnt(1)
	v_max_f32_e32 v8, v8, v8
	s_waitcnt lgkmcnt(0)
	v_max_f32_e32 v9, v9, v9
	ds_bpermute_b32 v10, v12, v6
	ds_bpermute_b32 v11, v12, v7
	v_max_f32_e32 v4, v4, v8
	v_max_f32_e32 v5, v5, v9
	ds_bpermute_b32 v8, v12, v4
	ds_bpermute_b32 v9, v12, v5
	s_waitcnt lgkmcnt(3)
	v_add_f32_e32 v130, v6, v10
	s_waitcnt lgkmcnt(2)
	v_add_f32_e32 v6, v7, v11
	ds_bpermute_b32 v7, v13, v6
	s_waitcnt lgkmcnt(2)
	v_max_f32_e32 v8, v8, v8
	s_waitcnt lgkmcnt(1)
	v_max_f32_e32 v9, v9, v9
	v_max_f32_e32 v4, v4, v8
	v_max_f32_e32 v5, v5, v9
	ds_bpermute_b32 v8, v13, v4
	ds_bpermute_b32 v9, v13, v5
	s_waitcnt lgkmcnt(2)
	v_add_f32_e32 v6, v6, v7
	v_mul_f32_e32 v6, 0x3fb8aa3b, v6
	v_exp_f32_e32 v129, v6
	s_waitcnt lgkmcnt(1)
	v_max_f32_e32 v6, v8, v8
	s_waitcnt lgkmcnt(0)
	v_max_f32_e32 v7, v9, v9
	v_max_f32_e32 v4, v4, v6
	v_max_f32_e32 v5, v5, v7
	v_mul_f32_e32 v4, v4, v5
	v_mul_f32_e32 v4, 0x4138aa3b, v4
	v_fma_f32 v8, v4, s18, 0.5
	v_mad_i64_i32 v[4:5], s[18:19], v108, s14, v[2:3]
	v_mad_i64_i32 v[2:3], s[18:19], v106, s14, v[2:3]
	global_load_dwordx4 v[58:61], v[4:5], off
	global_load_dwordx4 v[50:53], v[4:5], off offset:64
	global_load_dwordx4 v[62:65], v[2:3], off
	global_load_dwordx4 v[54:57], v[2:3], off offset:64
	v_ashrrev_i32_e32 v2, 3, v124
	v_ashrrev_i32_e32 v3, 31, v2
	v_mad_i64_i32 v[4:5], s[18:19], s20, v1, v[2:3]
	v_mad_u64_u32 v[6:7], s[18:19], v4, s14, v[100:101]
	s_mul_hi_i32 s18, s20, 0x300
	s_mulk_i32 s20, 0x300
	s_add_u32 s4, s20, s4
	v_lshrrev_b32_e32 v9, 4, v124
	s_addc_u32 s5, s18, s5
	v_xor_b32_e32 v10, v9, v124
	v_lshl_add_u64 v[2:3], s[4:5], 0, v[2:3]
	v_lshlrev_b32_e32 v4, 4, v10
	v_mad_u64_u32 v[112:113], s[4:5], v2, s15, v[102:103]
	v_and_b32_e32 v98, 0x70, v4
	v_mad_i32_i24 v113, v3, s15, v113
	v_mad_i32_i24 v7, v5, s14, v7
	v_lshl_add_u64 v[2:3], v[112:113], 0, v[98:99]
	s_mov_b64 s[4:5], 0x88000
	v_lshl_add_u64 v[110:111], v[6:7], 0, s[12:13]
	v_lshl_add_u64 v[6:7], v[2:3], 0, s[4:5]
	v_readfirstlane_b32 s4, v14
	s_lshl_b32 s4, s4, 10
	s_add_i32 s4, s4, 0
	v_lshl_add_u64 v[4:5], v[110:111], 0, v[98:99]
	s_mov_b32 m0, s4
	ds_bpermute_b32 v131, v13, v130
	global_load_lds_dwordx4 v[4:5], off
	v_lshl_add_u64 v[4:5], v[4:5], 0, s[2:3]
	s_add_i32 m0, s4, 0x2000
	v_xor_b32_e32 v90, 0x80000000, v8
	global_load_lds_dwordx4 v[4:5], off
	s_add_i32 m0, s4, 0x4000
	v_bfe_u32 v4, v124, 1, 3
	global_load_lds_dwordx4 v[2:3], off
	s_add_i32 m0, s4, 0x6000
	v_lshrrev_b32_e32 v3, 1, v124
	global_load_lds_dwordx4 v[6:7], off
	v_lshlrev_b32_e32 v2, 7, v15
	v_bitop3_b32 v3, v121, v3, 7 bitop3:0x78
	v_lshl_or_b32 v133, v3, 4, v2
	v_bitop3_b32 v3, v121, v4, 4 bitop3:0x36
	v_lshl_or_b32 v132, v3, 4, v2
	v_bitop3_b32 v2, v9, 7, v124 bitop3:0x48
	v_mov_b32_e32 v91, v90
	v_mov_b32_e32 v92, v90
	v_mov_b32_e32 v93, v90
	v_lshlrev_b32_e32 v98, 4, v2
	s_mov_b32 s5, 0
	v_mov_b32_e32 v2, v99
	v_mov_b32_e32 v3, v99
	v_mov_b32_e32 v4, v99
	v_mov_b32_e32 v5, v99
	v_mov_b32_e32 v6, v99
	v_mov_b32_e32 v7, v99
	v_mov_b32_e32 v8, v99
	v_mov_b32_e32 v9, v99
	v_mov_b32_e32 v10, v99
	v_mov_b32_e32 v11, v99
	v_mov_b32_e32 v12, v99
	v_mov_b32_e32 v13, v99
	v_mov_b32_e32 v40, v99
	v_mov_b32_e32 v41, v99
	v_mov_b32_e32 v42, v99
	v_mov_b32_e32 v43, v99
	v_mov_b32_e32 v44, v99
	v_mov_b32_e32 v45, v99
	v_mov_b32_e32 v46, v99
	v_mov_b32_e32 v47, v99
	v_mov_b32_e32 v48, v99
	v_mov_b32_e32 v49, v99
	v_mov_b32_e32 v66, v99
	v_mov_b32_e32 v67, v99
	v_mov_b32_e32 v68, v99
	v_mov_b32_e32 v69, v99
	v_mov_b32_e32 v70, v99
	v_mov_b32_e32 v71, v99
	v_mov_b32_e32 v72, v99
	v_mov_b32_e32 v73, v99
	v_mov_b32_e32 v74, v99
	v_mov_b32_e32 v75, v99
	v_mov_b32_e32 v76, v99
	v_mov_b32_e32 v77, v99
	v_mov_b32_e32 v78, v99
	v_mov_b32_e32 v79, v99
	v_mov_b32_e32 v80, v99
	v_mov_b32_e32 v81, v99
	v_mov_b32_e32 v82, v99
	v_mov_b32_e32 v83, v99
	v_mov_b32_e32 v84, v99
	v_mov_b32_e32 v85, v99
	v_mov_b32_e32 v86, v99
	v_mov_b32_e32 v87, v99
	v_mov_b32_e32 v88, v99
	v_mov_b32_e32 v89, v99
	v_mov_b32_e32 v14, v99
	v_mov_b32_e32 v15, v99
	v_mov_b32_e32 v16, v99
	v_mov_b32_e32 v17, v99
	v_mov_b32_e32 v22, v99
	v_mov_b32_e32 v23, v99
	v_mov_b32_e32 v24, v99
	v_mov_b32_e32 v25, v99
	v_readlane_b32 s57, v196, 7
	v_readlane_b32 s58, v196, 8
	v_readlane_b32 s59, v196, 9
	v_readlane_b32 s62, v196, 12
	v_readlane_b32 s63, v196, 13
	v_readlane_b32 s64, v196, 14
	v_readlane_b32 s65, v196, 15
	v_readlane_b32 s66, v196, 16
	v_readlane_b32 s67, v196, 17
	v_readlane_b32 s68, v196, 18
	v_readlane_b32 s69, v196, 19
	v_readlane_b32 s70, v196, 20
	v_readlane_b32 s71, v196, 21
	s_waitcnt vmcnt(0) lgkmcnt(0)
	s_barrier
	v_lshl_add_u64 v[248:249], v[110:111], 0, v[98:99]
	v_lshl_add_u64 v[252:253], v[112:113], 0, v[98:99]
	s_mov_b64 s[26:27], 0x88000
	v_lshl_add_u64 v[248:249], v[248:249], 0, s[6:7]
	v_lshl_add_u64 v[252:253], v[252:253], 0, s[2:3]
	v_lshl_add_u64 v[250:251], v[248:249], 0, s[2:3]
	v_lshl_add_u64 v[254:255], v[252:253], 0, s[26:27]
	v_mov_b32_e32 v244, s8
	v_mov_b32_e32 v245, s9
	v_mov_b32_e32 v246, s10
	v_mov_b32_e32 v247, s11
	s_mov_b32 s20, 0x8000
	s_mov_b32 s21, 0
	s_mov_b32 s22, 0x10000
	s_mov_b32 s23, 0
	s_add_i32 s25, s4, s20
	s_mov_b32 m0, s25
	s_nop 0
	global_load_lds_dwordx4 v[248:249], off
	s_add_i32 m0, s25, 0x2000
	s_nop 0
	global_load_lds_dwordx4 v[250:251], off
	s_add_i32 m0, s25, 0x4000
	s_nop 0
	global_load_lds_dwordx4 v[252:253], off
	s_add_i32 m0, s25, 0x6000
	s_nop 0
	global_load_lds_dwordx4 v[254:255], off
	v_lshl_add_u64 v[248:249], v[248:249], 0, s[6:7]
	v_lshl_add_u64 v[250:251], v[250:251], 0, s[6:7]
	v_lshl_add_u64 v[252:253], v[252:253], 0, s[2:3]
	v_lshl_add_u64 v[254:255], v[254:255], 0, s[2:3]
	v_add_u32_e32 v94, v134, v133
	v_add_u32_e32 v95, v134, v132
	ds_read_b128 v[204:207], v94
	ds_read_b128 v[208:211], v95
	ds_read_b128 v[212:215], v94 offset:2048
	ds_read_b128 v[216:219], v95 offset:2048
	s_waitcnt lgkmcnt(3)
	v_mfma_f32_16x16x32_bf16 v[136:139], v[204:207], v[58:61], v[90:93]
	v_mfma_f32_16x16x32_bf16 v[140:143], v[204:207], v[62:65], v[90:93]
	ds_read_b128 v[204:207], v94 offset:4096
	s_waitcnt lgkmcnt(3)
	v_mfma_f32_16x16x32_bf16 v[136:139], v[208:211], v[50:53], v[136:139]
	v_mfma_f32_16x16x32_bf16 v[140:143], v[208:211], v[54:57], v[140:143]
	ds_read_b128 v[208:211], v95 offset:4096
	s_waitcnt lgkmcnt(3)
	v_mfma_f32_16x16x32_bf16 v[144:147], v[212:215], v[58:61], v[90:93]
	v_mfma_f32_16x16x32_bf16 v[148:151], v[212:215], v[62:65], v[90:93]
	ds_read_b128 v[212:215], v94 offset:6144
	s_waitcnt lgkmcnt(3)
	v_mfma_f32_16x16x32_bf16 v[144:147], v[216:219], v[50:53], v[144:147]
	v_mfma_f32_16x16x32_bf16 v[148:151], v[216:219], v[54:57], v[148:151]
	ds_read_b128 v[216:219], v95 offset:6144
	s_waitcnt lgkmcnt(3)
	v_mfma_f32_16x16x32_bf16 v[152:155], v[204:207], v[58:61], v[90:93]
	v_mfma_f32_16x16x32_bf16 v[156:159], v[204:207], v[62:65], v[90:93]
	s_waitcnt lgkmcnt(2)
	v_mfma_f32_16x16x32_bf16 v[152:155], v[208:211], v[50:53], v[152:155]
	v_mfma_f32_16x16x32_bf16 v[156:159], v[208:211], v[54:57], v[156:159]
	s_waitcnt lgkmcnt(1)
	v_mfma_f32_16x16x32_bf16 v[160:163], v[212:215], v[58:61], v[90:93]
	v_mfma_f32_16x16x32_bf16 v[164:167], v[212:215], v[62:65], v[90:93]
	s_waitcnt lgkmcnt(0)
	v_mfma_f32_16x16x32_bf16 v[160:163], v[216:219], v[50:53], v[160:163]
	v_mfma_f32_16x16x32_bf16 v[164:167], v[216:219], v[54:57], v[164:167]
	s_waitcnt vmcnt(0) lgkmcnt(0)
	s_barrier
.Lattn_loop:
	v_add3_u32 v94, s20, v134, v133
	v_add3_u32 v95, s20, v134, v132
	ds_read_b128 v[204:207], v94
	ds_read_b128 v[208:211], v95
	ds_read_b128 v[212:215], v94 offset:2048
	ds_read_b128 v[216:219], v95 offset:2048
	v_add_u32_e32 v96, s21, v133
	v_add_u32_e32 v97, s21, v132
	s_add_i32 s25, s4, s22
	s_waitcnt lgkmcnt(3)
	v_mfma_f32_16x16x32_bf16 v[168:171], v[204:207], v[58:61], v[90:93]
	v_exp_f32_e32 v136, v136
	v_mfma_f32_16x16x32_bf16 v[172:175], v[204:207], v[62:65], v[90:93]
	v_exp_f32_e32 v137, v137
	ds_read_b128 v[204:207], v94 offset:4096
	s_waitcnt lgkmcnt(3)
	v_mfma_f32_16x16x32_bf16 v[168:171], v[208:211], v[50:53], v[168:171]
	v_exp_f32_e32 v138, v138
	s_mov_b32 m0, s25
	s_nop 0
	global_load_lds_dwordx4 v[248:249], off
	v_mfma_f32_16x16x32_bf16 v[172:175], v[208:211], v[54:57], v[172:175]
	v_exp_f32_e32 v139, v139
	ds_read_b128 v[208:211], v95 offset:4096
	s_waitcnt lgkmcnt(3)
	v_mfma_f32_16x16x32_bf16 v[176:179], v[212:215], v[58:61], v[90:93]
	v_exp_f32_e32 v144, v144
	s_add_i32 m0, s25, 0x2000
	s_nop 0
	global_load_lds_dwordx4 v[250:251], off
	v_mfma_f32_16x16x32_bf16 v[180:183], v[212:215], v[62:65], v[90:93]
	v_exp_f32_e32 v145, v145
	ds_read_b128 v[212:215], v94 offset:6144
	s_waitcnt lgkmcnt(3)
	v_mfma_f32_16x16x32_bf16 v[176:179], v[216:219], v[50:53], v[176:179]
	v_exp_f32_e32 v146, v146
	s_add_i32 m0, s25, 0x4000
	s_nop 0
	global_load_lds_dwordx4 v[252:253], off
	v_mfma_f32_16x16x32_bf16 v[180:183], v[216:219], v[54:57], v[180:183]
	v_exp_f32_e32 v147, v147
	ds_read_b128 v[216:219], v95 offset:6144
	s_waitcnt lgkmcnt(3)
	v_mfma_f32_16x16x32_bf16 v[184:187], v[204:207], v[58:61], v[90:93]
	v_exp_f32_e32 v140, v140
	s_add_i32 m0, s25, 0x6000
	s_nop 0
	global_load_lds_dwordx4 v[254:255], off
	v_mfma_f32_16x16x32_bf16 v[188:191], v[204:207], v[62:65], v[90:93]
	v_exp_f32_e32 v141, v141
	v_cvt_pk_bf16_f32 v136, v136, v137
	ds_read_b128 v[220:223], v96 offset:16384
	s_waitcnt lgkmcnt(3)
	v_mfma_f32_16x16x32_bf16 v[184:187], v[208:211], v[50:53], v[184:187]
	v_exp_f32_e32 v142, v142
	v_cvt_pk_bf16_f32 v137, v138, v139
	ds_read_b128 v[224:227], v96 offset:18432
	v_mfma_f32_16x16x32_bf16 v[188:191], v[208:211], v[54:57], v[188:191]
	v_exp_f32_e32 v143, v143
	v_cvt_pk_bf16_f32 v138, v144, v145
	ds_read_b128 v[228:231], v96 offset:20480
	s_waitcnt lgkmcnt(4)
	v_mfma_f32_16x16x32_bf16 v[192:195], v[212:215], v[58:61], v[90:93]
	v_exp_f32_e32 v148, v148
	v_cvt_pk_bf16_f32 v139, v146, v147
	ds_read_b128 v[232:235], v96 offset:22528
	v_mfma_f32_16x16x32_bf16 v[200:203], v[212:215], v[62:65], v[90:93]
	v_exp_f32_e32 v149, v149
	v_lshl_add_u64 v[248:249], v[248:249], 0, s[6:7]
	v_lshl_add_u64 v[250:251], v[250:251], 0, s[6:7]
	v_cvt_pk_bf16_f32 v140, v140, v141
	s_waitcnt lgkmcnt(4)
	v_mfma_f32_16x16x32_bf16 v[192:195], v[216:219], v[50:53], v[192:195]
	v_exp_f32_e32 v150, v150
	v_lshl_add_u64 v[252:253], v[252:253], 0, s[2:3]
	v_lshl_add_u64 v[254:255], v[254:255], 0, s[2:3]
	v_cvt_pk_bf16_f32 v141, v142, v143
	v_mfma_f32_16x16x32_bf16 v[200:203], v[216:219], v[54:57], v[200:203]
	v_exp_f32_e32 v151, v151
	v_cvt_pk_bf16_f32 v142, v148, v149
	v_cvt_pk_bf16_f32 v143, v150, v151
	v_mfma_f32_16x16x32_bf16 v[86:89], v[244:247], v[136:139], v[86:89]
	v_exp_f32_e32 v152, v152
	ds_read_b128 v[236:239], v96 offset:24576
	v_mfma_f32_16x16x32_bf16 v[82:85], v[244:247], v[140:143], v[82:85]
	v_exp_f32_e32 v153, v153
	ds_read_b128 v[240:243], v96 offset:26624
	s_waitcnt lgkmcnt(5)
	v_mfma_f32_16x16x32_bf16 v[78:81], v[220:223], v[136:139], v[78:81]
	v_exp_f32_e32 v154, v154
	v_mfma_f32_16x16x32_bf16 v[74:77], v[220:223], v[140:143], v[74:77]
	v_exp_f32_e32 v155, v155
	ds_read_b128 v[220:223], v96 offset:28672
	s_waitcnt lgkmcnt(5)
	v_mfma_f32_16x16x32_bf16 v[70:73], v[224:227], v[136:139], v[70:73]
	v_exp_f32_e32 v160, v160
	v_mfma_f32_16x16x32_bf16 v[66:69], v[224:227], v[140:143], v[66:69]
	v_exp_f32_e32 v161, v161
	ds_read_b128 v[224:227], v96 offset:30720
	s_waitcnt lgkmcnt(5)
	v_mfma_f32_16x16x32_bf16 v[46:49], v[228:231], v[136:139], v[46:49]
	v_exp_f32_e32 v162, v162
	v_mfma_f32_16x16x32_bf16 v[42:45], v[228:231], v[140:143], v[42:45]
	v_exp_f32_e32 v163, v163
	ds_read_b128 v[228:231], v97 offset:16384
	s_waitcnt lgkmcnt(5)
	v_mfma_f32_16x16x32_bf16 v[38:41], v[232:235], v[136:139], v[38:41]
	v_exp_f32_e32 v156, v156
	v_cvt_pk_bf16_f32 v152, v152, v153
	v_mfma_f32_16x16x32_bf16 v[34:37], v[232:235], v[140:143], v[34:37]
	v_exp_f32_e32 v157, v157
	v_cvt_pk_bf16_f32 v153, v154, v155
	ds_read_b128 v[232:235], v97 offset:18432
	s_waitcnt lgkmcnt(5)
	v_mfma_f32_16x16x32_bf16 v[30:33], v[236:239], v[136:139], v[30:33]
	v_exp_f32_e32 v158, v158
	v_cvt_pk_bf16_f32 v154, v160, v161
	v_mfma_f32_16x16x32_bf16 v[26:29], v[236:239], v[140:143], v[26:29]
	v_exp_f32_e32 v159, v159
	v_cvt_pk_bf16_f32 v155, v162, v163
	ds_read_b128 v[236:239], v97 offset:20480
	s_waitcnt lgkmcnt(5)
	v_mfma_f32_16x16x32_bf16 v[18:21], v[240:243], v[136:139], v[18:21]
	v_exp_f32_e32 v164, v164
	v_cvt_pk_bf16_f32 v156, v156, v157
	v_mfma_f32_16x16x32_bf16 v[10:13], v[240:243], v[140:143], v[10:13]
	v_exp_f32_e32 v165, v165
	v_cvt_pk_bf16_f32 v157, v158, v159
	ds_read_b128 v[240:243], v97 offset:22528
	s_waitcnt lgkmcnt(5)
	v_mfma_f32_16x16x32_bf16 v[6:9], v[220:223], v[136:139], v[6:9]
	v_exp_f32_e32 v166, v166
	v_cvt_pk_bf16_f32 v158, v164, v165
	v_mfma_f32_16x16x32_bf16 v[2:5], v[220:223], v[140:143], v[2:5]
	v_exp_f32_e32 v167, v167
	ds_read_b128 v[220:223], v97 offset:24576
	s_waitcnt lgkmcnt(5)
	v_mfma_f32_16x16x32_bf16 v[14:17], v[224:227], v[136:139], v[14:17]
	v_cvt_pk_bf16_f32 v159, v166, v167
	v_mfma_f32_16x16x32_bf16 v[22:25], v[224:227], v[140:143], v[22:25]
	ds_read_b128 v[224:227], v97 offset:26624
	v_mfma_f32_16x16x32_bf16 v[86:89], v[244:247], v[152:155], v[86:89]
	v_mfma_f32_16x16x32_bf16 v[82:85], v[244:247], v[156:159], v[82:85]
	s_waitcnt lgkmcnt(5)
	v_mfma_f32_16x16x32_bf16 v[78:81], v[228:231], v[152:155], v[78:81]
	v_mfma_f32_16x16x32_bf16 v[74:77], v[228:231], v[156:159], v[74:77]
	ds_read_b128 v[228:231], v97 offset:28672
	s_waitcnt lgkmcnt(5)
	v_mfma_f32_16x16x32_bf16 v[70:73], v[232:235], v[152:155], v[70:73]
	v_mfma_f32_16x16x32_bf16 v[66:69], v[232:235], v[156:159], v[66:69]
	ds_read_b128 v[232:235], v97 offset:30720
	s_waitcnt lgkmcnt(5)
	v_mfma_f32_16x16x32_bf16 v[46:49], v[236:239], v[152:155], v[46:49]
	v_mfma_f32_16x16x32_bf16 v[42:45], v[236:239], v[156:159], v[42:45]
	s_waitcnt lgkmcnt(4)
	v_mfma_f32_16x16x32_bf16 v[38:41], v[240:243], v[152:155], v[38:41]
	v_mfma_f32_16x16x32_bf16 v[34:37], v[240:243], v[156:159], v[34:37]
	s_waitcnt lgkmcnt(3)
	v_mfma_f32_16x16x32_bf16 v[30:33], v[220:223], v[152:155], v[30:33]
	v_mfma_f32_16x16x32_bf16 v[26:29], v[220:223], v[156:159], v[26:29]
	s_waitcnt lgkmcnt(2)
	v_mfma_f32_16x16x32_bf16 v[18:21], v[224:227], v[152:155], v[18:21]
	v_mfma_f32_16x16x32_bf16 v[10:13], v[224:227], v[156:159], v[10:13]
	s_waitcnt lgkmcnt(1)
	v_mfma_f32_16x16x32_bf16 v[6:9], v[228:231], v[152:155], v[6:9]
	v_mfma_f32_16x16x32_bf16 v[2:5], v[228:231], v[156:159], v[2:5]
	s_waitcnt lgkmcnt(0)
	v_mfma_f32_16x16x32_bf16 v[14:17], v[232:235], v[152:155], v[14:17]
	v_mfma_f32_16x16x32_bf16 v[22:25], v[232:235], v[156:159], v[22:25]
	s_waitcnt vmcnt(0) lgkmcnt(0)
	s_barrier
	s_mov_b32 s24, s21
	s_mov_b32 s21, s20
	s_mov_b32 s20, s22
	s_mov_b32 s22, s24
	v_add3_u32 v94, s20, v134, v133
	v_add3_u32 v95, s20, v134, v132
	ds_read_b128 v[204:207], v94
	ds_read_b128 v[208:211], v95
	ds_read_b128 v[212:215], v94 offset:2048
	ds_read_b128 v[216:219], v95 offset:2048
	v_add_u32_e32 v96, s21, v133
	v_add_u32_e32 v97, s21, v132
	s_add_i32 s25, s4, s22
	s_waitcnt lgkmcnt(3)
	v_mfma_f32_16x16x32_bf16 v[136:139], v[204:207], v[58:61], v[90:93]
	v_exp_f32_e32 v168, v168
	v_mfma_f32_16x16x32_bf16 v[140:143], v[204:207], v[62:65], v[90:93]
	v_exp_f32_e32 v169, v169
	ds_read_b128 v[204:207], v94 offset:4096
	s_waitcnt lgkmcnt(3)
	v_mfma_f32_16x16x32_bf16 v[136:139], v[208:211], v[50:53], v[136:139]
	v_exp_f32_e32 v170, v170
	s_mov_b32 m0, s25
	s_nop 0
	global_load_lds_dwordx4 v[248:249], off
	v_mfma_f32_16x16x32_bf16 v[140:143], v[208:211], v[54:57], v[140:143]
	v_exp_f32_e32 v171, v171
	ds_read_b128 v[208:211], v95 offset:4096
	s_waitcnt lgkmcnt(3)
	v_mfma_f32_16x16x32_bf16 v[144:147], v[212:215], v[58:61], v[90:93]
	v_exp_f32_e32 v176, v176
	s_add_i32 m0, s25, 0x2000
	s_nop 0
	global_load_lds_dwordx4 v[250:251], off
	v_mfma_f32_16x16x32_bf16 v[148:151], v[212:215], v[62:65], v[90:93]
	v_exp_f32_e32 v177, v177
	ds_read_b128 v[212:215], v94 offset:6144
	s_waitcnt lgkmcnt(3)
	v_mfma_f32_16x16x32_bf16 v[144:147], v[216:219], v[50:53], v[144:147]
	v_exp_f32_e32 v178, v178
	s_add_i32 m0, s25, 0x4000
	s_nop 0
	global_load_lds_dwordx4 v[252:253], off
	v_mfma_f32_16x16x32_bf16 v[148:151], v[216:219], v[54:57], v[148:151]
	v_exp_f32_e32 v179, v179
	ds_read_b128 v[216:219], v95 offset:6144
	s_waitcnt lgkmcnt(3)
	v_mfma_f32_16x16x32_bf16 v[152:155], v[204:207], v[58:61], v[90:93]
	v_exp_f32_e32 v172, v172
	s_add_i32 m0, s25, 0x6000
	s_nop 0
	global_load_lds_dwordx4 v[254:255], off
	v_mfma_f32_16x16x32_bf16 v[156:159], v[204:207], v[62:65], v[90:93]
	v_exp_f32_e32 v173, v173
	v_cvt_pk_bf16_f32 v168, v168, v169
	ds_read_b128 v[220:223], v96 offset:16384
	s_waitcnt lgkmcnt(3)
	v_mfma_f32_16x16x32_bf16 v[152:155], v[208:211], v[50:53], v[152:155]
	v_exp_f32_e32 v174, v174
	v_cvt_pk_bf16_f32 v169, v170, v171
	ds_read_b128 v[224:227], v96 offset:18432
	v_mfma_f32_16x16x32_bf16 v[156:159], v[208:211], v[54:57], v[156:159]
	v_exp_f32_e32 v175, v175
	v_cvt_pk_bf16_f32 v170, v176, v177
	ds_read_b128 v[228:231], v96 offset:20480
	s_waitcnt lgkmcnt(4)
	v_mfma_f32_16x16x32_bf16 v[160:163], v[212:215], v[58:61], v[90:93]
	v_exp_f32_e32 v180, v180
	v_cvt_pk_bf16_f32 v171, v178, v179
	ds_read_b128 v[232:235], v96 offset:22528
	v_mfma_f32_16x16x32_bf16 v[164:167], v[212:215], v[62:65], v[90:93]
	v_exp_f32_e32 v181, v181
	v_lshl_add_u64 v[248:249], v[248:249], 0, s[6:7]
	v_lshl_add_u64 v[250:251], v[250:251], 0, s[6:7]
	v_cvt_pk_bf16_f32 v172, v172, v173
	s_waitcnt lgkmcnt(4)
	v_mfma_f32_16x16x32_bf16 v[160:163], v[216:219], v[50:53], v[160:163]
	v_exp_f32_e32 v182, v182
	v_lshl_add_u64 v[252:253], v[252:253], 0, s[2:3]
	v_lshl_add_u64 v[254:255], v[254:255], 0, s[2:3]
	v_cvt_pk_bf16_f32 v173, v174, v175
	v_mfma_f32_16x16x32_bf16 v[164:167], v[216:219], v[54:57], v[164:167]
	v_exp_f32_e32 v183, v183
	v_cvt_pk_bf16_f32 v174, v180, v181
	v_cvt_pk_bf16_f32 v175, v182, v183
	v_mfma_f32_16x16x32_bf16 v[86:89], v[244:247], v[168:171], v[86:89]
	v_exp_f32_e32 v184, v184
	ds_read_b128 v[236:239], v96 offset:24576
	v_mfma_f32_16x16x32_bf16 v[82:85], v[244:247], v[172:175], v[82:85]
	v_exp_f32_e32 v185, v185
	ds_read_b128 v[240:243], v96 offset:26624
	s_waitcnt lgkmcnt(5)
	v_mfma_f32_16x16x32_bf16 v[78:81], v[220:223], v[168:171], v[78:81]
	v_exp_f32_e32 v186, v186
	v_mfma_f32_16x16x32_bf16 v[74:77], v[220:223], v[172:175], v[74:77]
	v_exp_f32_e32 v187, v187
	ds_read_b128 v[220:223], v96 offset:28672
	s_waitcnt lgkmcnt(5)
	v_mfma_f32_16x16x32_bf16 v[70:73], v[224:227], v[168:171], v[70:73]
	v_exp_f32_e32 v192, v192
	v_mfma_f32_16x16x32_bf16 v[66:69], v[224:227], v[172:175], v[66:69]
	v_exp_f32_e32 v193, v193
	ds_read_b128 v[224:227], v96 offset:30720
	s_waitcnt lgkmcnt(5)
	v_mfma_f32_16x16x32_bf16 v[46:49], v[228:231], v[168:171], v[46:49]
	v_exp_f32_e32 v194, v194
	v_mfma_f32_16x16x32_bf16 v[42:45], v[228:231], v[172:175], v[42:45]
	v_exp_f32_e32 v195, v195
	ds_read_b128 v[228:231], v97 offset:16384
	s_waitcnt lgkmcnt(5)
	v_mfma_f32_16x16x32_bf16 v[38:41], v[232:235], v[168:171], v[38:41]
	v_exp_f32_e32 v188, v188
	v_cvt_pk_bf16_f32 v184, v184, v185
	v_mfma_f32_16x16x32_bf16 v[34:37], v[232:235], v[172:175], v[34:37]
	v_exp_f32_e32 v189, v189
	v_cvt_pk_bf16_f32 v185, v186, v187
	ds_read_b128 v[232:235], v97 offset:18432
	s_waitcnt lgkmcnt(5)
	v_mfma_f32_16x16x32_bf16 v[30:33], v[236:239], v[168:171], v[30:33]
	v_exp_f32_e32 v190, v190
	v_cvt_pk_bf16_f32 v186, v192, v193
	v_mfma_f32_16x16x32_bf16 v[26:29], v[236:239], v[172:175], v[26:29]
	v_exp_f32_e32 v191, v191
	v_cvt_pk_bf16_f32 v187, v194, v195
	ds_read_b128 v[236:239], v97 offset:20480
	s_waitcnt lgkmcnt(5)
	v_mfma_f32_16x16x32_bf16 v[18:21], v[240:243], v[168:171], v[18:21]
	v_exp_f32_e32 v200, v200
	v_cvt_pk_bf16_f32 v188, v188, v189
	v_mfma_f32_16x16x32_bf16 v[10:13], v[240:243], v[172:175], v[10:13]
	v_exp_f32_e32 v201, v201
	v_cvt_pk_bf16_f32 v189, v190, v191
	ds_read_b128 v[240:243], v97 offset:22528
	s_waitcnt lgkmcnt(5)
	v_mfma_f32_16x16x32_bf16 v[6:9], v[220:223], v[168:171], v[6:9]
	v_exp_f32_e32 v202, v202
	v_cvt_pk_bf16_f32 v190, v200, v201
	v_mfma_f32_16x16x32_bf16 v[2:5], v[220:223], v[172:175], v[2:5]
	v_exp_f32_e32 v203, v203
	ds_read_b128 v[220:223], v97 offset:24576
	s_waitcnt lgkmcnt(5)
	v_mfma_f32_16x16x32_bf16 v[14:17], v[224:227], v[168:171], v[14:17]
	v_cvt_pk_bf16_f32 v191, v202, v203
	v_mfma_f32_16x16x32_bf16 v[22:25], v[224:227], v[172:175], v[22:25]
	ds_read_b128 v[224:227], v97 offset:26624
	v_mfma_f32_16x16x32_bf16 v[86:89], v[244:247], v[184:187], v[86:89]
	v_mfma_f32_16x16x32_bf16 v[82:85], v[244:247], v[188:191], v[82:85]
	s_waitcnt lgkmcnt(5)
	v_mfma_f32_16x16x32_bf16 v[78:81], v[228:231], v[184:187], v[78:81]
	v_mfma_f32_16x16x32_bf16 v[74:77], v[228:231], v[188:191], v[74:77]
	ds_read_b128 v[228:231], v97 offset:28672
	s_waitcnt lgkmcnt(5)
	v_mfma_f32_16x16x32_bf16 v[70:73], v[232:235], v[184:187], v[70:73]
	v_mfma_f32_16x16x32_bf16 v[66:69], v[232:235], v[188:191], v[66:69]
	ds_read_b128 v[232:235], v97 offset:30720
	s_waitcnt lgkmcnt(5)
	v_mfma_f32_16x16x32_bf16 v[46:49], v[236:239], v[184:187], v[46:49]
	v_mfma_f32_16x16x32_bf16 v[42:45], v[236:239], v[188:191], v[42:45]
	s_waitcnt lgkmcnt(4)
	v_mfma_f32_16x16x32_bf16 v[38:41], v[240:243], v[184:187], v[38:41]
	v_mfma_f32_16x16x32_bf16 v[34:37], v[240:243], v[188:191], v[34:37]
	s_waitcnt lgkmcnt(3)
	v_mfma_f32_16x16x32_bf16 v[30:33], v[220:223], v[184:187], v[30:33]
	v_mfma_f32_16x16x32_bf16 v[26:29], v[220:223], v[188:191], v[26:29]
	s_waitcnt lgkmcnt(2)
	v_mfma_f32_16x16x32_bf16 v[18:21], v[224:227], v[184:187], v[18:21]
	v_mfma_f32_16x16x32_bf16 v[10:13], v[224:227], v[188:191], v[10:13]
	s_waitcnt lgkmcnt(1)
	v_mfma_f32_16x16x32_bf16 v[6:9], v[228:231], v[184:187], v[6:9]
	v_mfma_f32_16x16x32_bf16 v[2:5], v[228:231], v[188:191], v[2:5]
	s_waitcnt lgkmcnt(0)
	v_mfma_f32_16x16x32_bf16 v[14:17], v[232:235], v[184:187], v[14:17]
	v_mfma_f32_16x16x32_bf16 v[22:25], v[232:235], v[188:191], v[22:25]
	s_waitcnt vmcnt(0) lgkmcnt(0)
	s_barrier
	s_mov_b32 s24, s21
	s_mov_b32 s21, s20
	s_mov_b32 s20, s22
	s_mov_b32 s22, s24
	s_add_i32 s23, s23, 1
	s_cmp_lg_u32 s23, 33
	s_cbranch_scc1 .Lattn_loop
	v_add_u32_e32 v96, s21, v133
	v_add_u32_e32 v97, s21, v132
	v_exp_f32_e32 v136, v136
	v_exp_f32_e32 v137, v137
	v_exp_f32_e32 v138, v138
	v_exp_f32_e32 v139, v139
	v_exp_f32_e32 v144, v144
	v_exp_f32_e32 v145, v145
	v_exp_f32_e32 v146, v146
	v_exp_f32_e32 v147, v147
	v_exp_f32_e32 v140, v140
	v_exp_f32_e32 v141, v141
	v_cvt_pk_bf16_f32 v136, v136, v137
	ds_read_b128 v[220:223], v96 offset:16384
	v_exp_f32_e32 v142, v142
	v_cvt_pk_bf16_f32 v137, v138, v139
	ds_read_b128 v[224:227], v96 offset:18432
	v_exp_f32_e32 v143, v143
	v_cvt_pk_bf16_f32 v138, v144, v145
	ds_read_b128 v[228:231], v96 offset:20480
	v_exp_f32_e32 v148, v148
	v_cvt_pk_bf16_f32 v139, v146, v147
	ds_read_b128 v[232:235], v96 offset:22528
	v_exp_f32_e32 v149, v149
	v_cvt_pk_bf16_f32 v140, v140, v141
	v_exp_f32_e32 v150, v150
	v_cvt_pk_bf16_f32 v141, v142, v143
	v_exp_f32_e32 v151, v151
	v_cvt_pk_bf16_f32 v142, v148, v149
	v_cvt_pk_bf16_f32 v143, v150, v151
	v_mfma_f32_16x16x32_bf16 v[86:89], v[244:247], v[136:139], v[86:89]
	v_exp_f32_e32 v152, v152
	ds_read_b128 v[236:239], v96 offset:24576
	v_mfma_f32_16x16x32_bf16 v[82:85], v[244:247], v[140:143], v[82:85]
	v_exp_f32_e32 v153, v153
	ds_read_b128 v[240:243], v96 offset:26624
	s_waitcnt lgkmcnt(5)
	v_mfma_f32_16x16x32_bf16 v[78:81], v[220:223], v[136:139], v[78:81]
	v_exp_f32_e32 v154, v154
	v_mfma_f32_16x16x32_bf16 v[74:77], v[220:223], v[140:143], v[74:77]
	v_exp_f32_e32 v155, v155
	ds_read_b128 v[220:223], v96 offset:28672
	s_waitcnt lgkmcnt(5)
	v_mfma_f32_16x16x32_bf16 v[70:73], v[224:227], v[136:139], v[70:73]
	v_exp_f32_e32 v160, v160
	v_mfma_f32_16x16x32_bf16 v[66:69], v[224:227], v[140:143], v[66:69]
	v_exp_f32_e32 v161, v161
	ds_read_b128 v[224:227], v96 offset:30720
	s_waitcnt lgkmcnt(5)
	v_mfma_f32_16x16x32_bf16 v[46:49], v[228:231], v[136:139], v[46:49]
	v_exp_f32_e32 v162, v162
	v_mfma_f32_16x16x32_bf16 v[42:45], v[228:231], v[140:143], v[42:45]
	v_exp_f32_e32 v163, v163
	ds_read_b128 v[228:231], v97 offset:16384
	s_waitcnt lgkmcnt(5)
	v_mfma_f32_16x16x32_bf16 v[38:41], v[232:235], v[136:139], v[38:41]
	v_exp_f32_e32 v156, v156
	v_cvt_pk_bf16_f32 v152, v152, v153
	v_mfma_f32_16x16x32_bf16 v[34:37], v[232:235], v[140:143], v[34:37]
	v_exp_f32_e32 v157, v157
	v_cvt_pk_bf16_f32 v153, v154, v155
	ds_read_b128 v[232:235], v97 offset:18432
	s_waitcnt lgkmcnt(5)
	v_mfma_f32_16x16x32_bf16 v[30:33], v[236:239], v[136:139], v[30:33]
	v_exp_f32_e32 v158, v158
	v_cvt_pk_bf16_f32 v154, v160, v161
	v_mfma_f32_16x16x32_bf16 v[26:29], v[236:239], v[140:143], v[26:29]
	v_exp_f32_e32 v159, v159
	v_cvt_pk_bf16_f32 v155, v162, v163
	ds_read_b128 v[236:239], v97 offset:20480
	s_waitcnt lgkmcnt(5)
	v_mfma_f32_16x16x32_bf16 v[18:21], v[240:243], v[136:139], v[18:21]
	v_exp_f32_e32 v164, v164
	v_cvt_pk_bf16_f32 v156, v156, v157
	v_mfma_f32_16x16x32_bf16 v[10:13], v[240:243], v[140:143], v[10:13]
	v_exp_f32_e32 v165, v165
	v_cvt_pk_bf16_f32 v157, v158, v159
	ds_read_b128 v[240:243], v97 offset:22528
	s_waitcnt lgkmcnt(5)
	v_mfma_f32_16x16x32_bf16 v[6:9], v[220:223], v[136:139], v[6:9]
	v_exp_f32_e32 v166, v166
	v_cvt_pk_bf16_f32 v158, v164, v165
	v_mfma_f32_16x16x32_bf16 v[2:5], v[220:223], v[140:143], v[2:5]
	v_exp_f32_e32 v167, v167
	ds_read_b128 v[220:223], v97 offset:24576
	s_waitcnt lgkmcnt(5)
	v_mfma_f32_16x16x32_bf16 v[14:17], v[224:227], v[136:139], v[14:17]
	v_cvt_pk_bf16_f32 v159, v166, v167
	v_mfma_f32_16x16x32_bf16 v[22:25], v[224:227], v[140:143], v[22:25]
	ds_read_b128 v[224:227], v97 offset:26624
	v_mfma_f32_16x16x32_bf16 v[86:89], v[244:247], v[152:155], v[86:89]
	v_mfma_f32_16x16x32_bf16 v[82:85], v[244:247], v[156:159], v[82:85]
	s_waitcnt lgkmcnt(5)
	v_mfma_f32_16x16x32_bf16 v[78:81], v[228:231], v[152:155], v[78:81]
	v_mfma_f32_16x16x32_bf16 v[74:77], v[228:231], v[156:159], v[74:77]
	ds_read_b128 v[228:231], v97 offset:28672
	s_waitcnt lgkmcnt(5)
	v_mfma_f32_16x16x32_bf16 v[70:73], v[232:235], v[152:155], v[70:73]
	v_mfma_f32_16x16x32_bf16 v[66:69], v[232:235], v[156:159], v[66:69]
	ds_read_b128 v[232:235], v97 offset:30720
	s_waitcnt lgkmcnt(5)
	v_mfma_f32_16x16x32_bf16 v[46:49], v[236:239], v[152:155], v[46:49]
	v_mfma_f32_16x16x32_bf16 v[42:45], v[236:239], v[156:159], v[42:45]
	s_waitcnt lgkmcnt(4)
	v_mfma_f32_16x16x32_bf16 v[38:41], v[240:243], v[152:155], v[38:41]
	v_mfma_f32_16x16x32_bf16 v[34:37], v[240:243], v[156:159], v[34:37]
	s_waitcnt lgkmcnt(3)
	v_mfma_f32_16x16x32_bf16 v[30:33], v[220:223], v[152:155], v[30:33]
	v_mfma_f32_16x16x32_bf16 v[26:29], v[220:223], v[156:159], v[26:29]
	s_waitcnt lgkmcnt(2)
	v_mfma_f32_16x16x32_bf16 v[18:21], v[224:227], v[152:155], v[18:21]
	v_mfma_f32_16x16x32_bf16 v[10:13], v[224:227], v[156:159], v[10:13]
	s_waitcnt lgkmcnt(1)
	v_mfma_f32_16x16x32_bf16 v[6:9], v[228:231], v[152:155], v[6:9]
	v_mfma_f32_16x16x32_bf16 v[2:5], v[228:231], v[156:159], v[2:5]
	s_waitcnt lgkmcnt(0)
	v_mfma_f32_16x16x32_bf16 v[14:17], v[232:235], v[152:155], v[14:17]
	v_mfma_f32_16x16x32_bf16 v[22:25], v[232:235], v[156:159], v[22:25]
	s_waitcnt lgkmcnt(0)

	v_add_u32_e32 v98, 0, v134
	v_add_u32_e32 v154, v98, v133
	ds_read_b128 v[94:97], v154 offset:32768
	v_add_u32_e32 v98, v98, v132
	ds_read_b128 v[134:137], v98 offset:32768
	ds_read_b128 v[142:145], v98 offset:34816
	ds_read_b128 v[150:153], v98 offset:36864
	s_waitcnt lgkmcnt(3)
	v_mfma_f32_16x16x32_bf16 v[110:113], v[94:97], v[58:61], v[90:93]
	v_mfma_f32_16x16x32_bf16 v[94:97], v[94:97], v[62:65], v[90:93]
	s_waitcnt lgkmcnt(2)
	v_mfma_f32_16x16x32_bf16 v[110:113], v[134:137], v[50:53], v[110:113]
	v_mfma_f32_16x16x32_bf16 v[94:97], v[134:137], v[54:57], v[94:97]
	ds_read_b128 v[134:137], v154 offset:34816
	s_waitcnt lgkmcnt(0)
	v_mfma_f32_16x16x32_bf16 v[138:141], v[134:137], v[58:61], v[90:93]
	v_mfma_f32_16x16x32_bf16 v[134:137], v[134:137], v[62:65], v[90:93]
	v_mfma_f32_16x16x32_bf16 v[138:141], v[142:145], v[50:53], v[138:141]
	v_mfma_f32_16x16x32_bf16 v[134:137], v[142:145], v[54:57], v[134:137]
	ds_read_b128 v[142:145], v154 offset:36864
	s_waitcnt lgkmcnt(0)
	v_mfma_f32_16x16x32_bf16 v[146:149], v[142:145], v[58:61], v[90:93]
	v_mfma_f32_16x16x32_bf16 v[142:145], v[142:145], v[62:65], v[90:93]
	v_mfma_f32_16x16x32_bf16 v[146:149], v[150:153], v[50:53], v[146:149]
	v_mfma_f32_16x16x32_bf16 v[142:145], v[150:153], v[54:57], v[142:145]
	ds_read_b128 v[150:153], v154 offset:38912
	s_waitcnt lgkmcnt(0)
	v_mfma_f32_16x16x32_bf16 v[58:61], v[150:153], v[58:61], v[90:93]
	v_mfma_f32_16x16x32_bf16 v[62:65], v[150:153], v[62:65], v[90:93]
	s_nop 2
	ds_read_b128 v[90:93], v98 offset:38912
	s_waitcnt lgkmcnt(0)
	v_mfma_f32_16x16x32_bf16 v[50:53], v[90:93], v[50:53], v[58:61]
	v_mfma_f32_16x16x32_bf16 v[60:63], v[90:93], v[54:57], v[62:65]
	v_exp_f32_e32 v54, v110
	v_exp_f32_e32 v55, v111
	v_exp_f32_e32 v56, v112
	v_exp_f32_e32 v57, v113
	v_exp_f32_e32 v58, v138
	v_exp_f32_e32 v59, v139
	v_exp_f32_e32 v64, v140
	v_exp_f32_e32 v65, v141
	v_exp_f32_e32 v98, v146
	v_exp_f32_e32 v110, v147
	v_exp_f32_e32 v111, v148
	v_exp_f32_e32 v112, v149
	v_exp_f32_e32 v50, v50
	v_exp_f32_e32 v51, v51
	v_exp_f32_e32 v52, v52
	v_exp_f32_e32 v53, v53
	v_cvt_pk_bf16_f32 v90, v54, v55
	v_cvt_pk_bf16_f32 v91, v56, v57
	v_cvt_pk_bf16_f32 v92, v58, v59
	v_cvt_pk_bf16_f32 v93, v64, v65
	v_cvt_pk_bf16_f32 v56, v98, v110
	v_cvt_pk_bf16_f32 v57, v111, v112
	v_cvt_pk_bf16_f32 v58, v50, v51
	v_cvt_pk_bf16_f32 v59, v52, v53
	v_exp_f32_e32 v50, v94
	v_exp_f32_e32 v51, v95
	v_exp_f32_e32 v52, v96
	v_exp_f32_e32 v53, v97
	v_exp_f32_e32 v54, v134
	v_exp_f32_e32 v55, v135
	v_exp_f32_e32 v64, v136
	v_exp_f32_e32 v65, v137
	v_exp_f32_e32 v98, v142
	v_exp_f32_e32 v110, v143
	v_exp_f32_e32 v111, v144
	v_exp_f32_e32 v112, v145
	v_exp_f32_e32 v60, v60
	v_exp_f32_e32 v61, v61
	v_exp_f32_e32 v62, v62
	v_exp_f32_e32 v63, v63
	v_cvt_pk_bf16_f32 v94, v50, v51
	v_cvt_pk_bf16_f32 v95, v52, v53
	v_cvt_pk_bf16_f32 v96, v54, v55
	v_cvt_pk_bf16_f32 v97, v64, v65
	v_cvt_pk_bf16_f32 v110, v98, v110
	v_cvt_pk_bf16_f32 v111, v111, v112
	v_cvt_pk_bf16_f32 v112, v60, v61
	v_cvt_pk_bf16_f32 v113, v62, v63
	v_mov_b64_e32 v[52:53], s[10:11]
	v_mov_b64_e32 v[50:51], s[8:9]
	s_nop 1
	v_mfma_f32_16x16x32_bf16 v[60:63], v[50:53], v[90:93], v[86:89]
	v_mfma_f32_16x16x32_bf16 v[82:85], v[50:53], v[94:97], v[82:85]
	v_mfma_f32_16x16x32_bf16 v[86:89], v[50:53], v[56:59], v[60:63]
	v_mfma_f32_16x16x32_bf16 v[50:53], v[50:53], v[110:113], v[82:85]
	s_nop 6
	v_add_u32_e32 v87, 0, v132
	v_add_u32_e32 v51, 0, v133
	ds_read_b128 v[52:55], v51 offset:49152
	s_waitcnt lgkmcnt(0)
	v_mfma_f32_16x16x32_bf16 v[60:63], v[52:55], v[90:93], v[78:81]
	v_mfma_f32_16x16x32_bf16 v[52:55], v[52:55], v[94:97], v[74:77]
	s_nop 2
	ds_read_b128 v[74:77], v87 offset:49152
	s_waitcnt lgkmcnt(0)
	v_mfma_f32_16x16x32_bf16 v[78:81], v[74:77], v[56:59], v[60:63]
	s_nop 2
	ds_read_b128 v[60:63], v51 offset:51200
	s_waitcnt lgkmcnt(0)
	v_mfma_f32_16x16x32_bf16 v[70:73], v[60:63], v[90:93], v[70:73]
	v_mfma_f32_16x16x32_bf16 v[60:63], v[60:63], v[94:97], v[66:69]
	s_nop 2
	ds_read_b128 v[64:67], v87 offset:51200
	v_mfma_f32_16x16x32_bf16 v[52:55], v[74:77], v[110:113], v[52:55]
	s_waitcnt lgkmcnt(0)
	v_mfma_f32_16x16x32_bf16 v[68:71], v[64:67], v[56:59], v[70:73]
	v_mfma_f32_16x16x32_bf16 v[60:63], v[64:67], v[110:113], v[60:63]
	ds_read_b128 v[64:67], v51 offset:53248
	s_waitcnt lgkmcnt(0)
	v_mfma_f32_16x16x32_bf16 v[46:49], v[64:67], v[90:93], v[46:49]
	v_mfma_f32_16x16x32_bf16 v[42:45], v[64:67], v[94:97], v[42:45]
	ds_read_b128 v[64:67], v87 offset:53248
	s_waitcnt lgkmcnt(0)
	v_mfma_f32_16x16x32_bf16 v[46:49], v[64:67], v[56:59], v[46:49]
	v_mfma_f32_16x16x32_bf16 v[42:45], v[64:67], v[110:113], v[42:45]
	ds_read_b128 v[64:67], v51 offset:55296
	s_waitcnt lgkmcnt(0)
	v_mfma_f32_16x16x32_bf16 v[38:41], v[64:67], v[90:93], v[38:41]
	v_mfma_f32_16x16x32_bf16 v[34:37], v[64:67], v[94:97], v[34:37]
	ds_read_b128 v[64:67], v87 offset:55296
	s_waitcnt lgkmcnt(0)
	v_mfma_f32_16x16x32_bf16 v[38:41], v[64:67], v[56:59], v[38:41]
	v_mfma_f32_16x16x32_bf16 v[34:37], v[64:67], v[110:113], v[34:37]
	ds_read_b128 v[64:67], v51 offset:57344
	s_waitcnt lgkmcnt(0)
	v_mfma_f32_16x16x32_bf16 v[30:33], v[64:67], v[90:93], v[30:33]
	v_mfma_f32_16x16x32_bf16 v[26:29], v[64:67], v[94:97], v[26:29]
	ds_read_b128 v[64:67], v87 offset:57344
	s_waitcnt lgkmcnt(0)
	v_mfma_f32_16x16x32_bf16 v[30:33], v[64:67], v[56:59], v[30:33]
	v_mfma_f32_16x16x32_bf16 v[26:29], v[64:67], v[110:113], v[26:29]
	ds_read_b128 v[64:67], v51 offset:59392
	s_waitcnt lgkmcnt(0)
	v_mfma_f32_16x16x32_bf16 v[18:21], v[64:67], v[90:93], v[18:21]
	v_mfma_f32_16x16x32_bf16 v[10:13], v[64:67], v[94:97], v[10:13]
	ds_read_b128 v[64:67], v87 offset:59392
	s_waitcnt lgkmcnt(0)
	v_mfma_f32_16x16x32_bf16 v[72:75], v[64:67], v[56:59], v[18:21]
	v_mfma_f32_16x16x32_bf16 v[132:135], v[64:67], v[110:113], v[10:13]
	s_nop 3
	ds_read_b128 v[10:13], v51 offset:61440
	s_waitcnt lgkmcnt(0)
	v_mfma_f32_16x16x32_bf16 v[6:9], v[10:13], v[90:93], v[6:9]
	v_mfma_f32_16x16x32_bf16 v[2:5], v[10:13], v[94:97], v[2:5]
	ds_read_b128 v[10:13], v87 offset:61440
	s_waitcnt lgkmcnt(0)
	v_mfma_f32_16x16x32_bf16 v[136:139], v[10:13], v[110:113], v[2:5]
	s_nop 4
	ds_read_b128 v[2:5], v51 offset:63488
	v_mfma_f32_16x16x32_bf16 v[82:85], v[10:13], v[56:59], v[6:9]
	ds_read_b128 v[10:13], v87 offset:63488
	s_waitcnt lgkmcnt(1)
	v_mfma_f32_16x16x32_bf16 v[6:9], v[2:5], v[90:93], v[14:17]
	v_mfma_f32_16x16x32_bf16 v[2:5], v[2:5], v[94:97], v[22:25]
	s_waitcnt lgkmcnt(0)
	v_mfma_f32_16x16x32_bf16 v[22:25], v[10:13], v[56:59], v[6:9]
	v_mfma_f32_16x16x32_bf16 v[88:91], v[10:13], v[110:113], v[2:5]
	s_nop 4
	v_div_scale_f32 v2, s[4:5], v86, v86, 1.0
	v_rcp_f32_e32 v3, v2
	s_barrier
	v_fma_f32 v4, -v2, v3, 1.0
	v_fmac_f32_e32 v3, v4, v3
	v_div_scale_f32 v4, vcc, 1.0, v86, 1.0
	v_mul_f32_e32 v5, v4, v3
	v_fma_f32 v6, -v2, v5, v4
	v_fmac_f32_e32 v5, v6, v3
	v_fma_f32 v2, -v2, v5, v4
	v_div_fmas_f32 v2, v2, v3, v5
	v_div_fixup_f32 v56, v2, v86, 1.0
	v_pk_mul_f32 v[18:19], v[56:57], v[30:31] op_sel_hi:[0,1]
	v_div_scale_f32 v30, s[4:5], v50, v50, 1.0
	v_rcp_f32_e32 v31, v30
	v_pk_mul_f32 v[10:11], v[56:57], v[46:47] op_sel_hi:[0,1]
	v_pk_mul_f32 v[46:47], v[56:57], v[84:85] op_sel_hi:[0,1]
	v_pk_mul_f32 v[84:85], v[56:57], v[22:23] op_sel_hi:[0,1]
	v_fma_f32 v22, -v30, v31, 1.0
	v_fmac_f32_e32 v31, v22, v31
	v_div_scale_f32 v22, vcc, 1.0, v50, 1.0
	v_mul_f32_e32 v23, v22, v31
	v_pk_mul_f32 v[66:67], v[56:57], v[24:25] op_sel_hi:[0,1]
	v_fma_f32 v24, -v30, v23, v22
	v_fmac_f32_e32 v23, v24, v31
	v_fma_f32 v22, -v30, v23, v22
	v_div_fmas_f32 v22, v22, v31, v23
	v_div_fixup_f32 v22, v22, v50, 1.0
	v_pk_mul_f32 v[4:5], v[56:57], v[80:81] op_sel_hi:[0,1]
	v_pk_mul_f32 v[6:7], v[56:57], v[78:79] op_sel_hi:[0,1]
	v_pk_mul_f32 v[2:3], v[56:57], v[70:71] op_sel_hi:[0,1]
	v_pk_mul_f32 v[12:13], v[56:57], v[68:69] op_sel_hi:[0,1]
	v_pk_mul_f32 v[8:9], v[56:57], v[48:49] op_sel_hi:[0,1]
	v_pk_mul_f32 v[16:17], v[56:57], v[40:41] op_sel_hi:[0,1]
	v_pk_mul_f32 v[20:21], v[56:57], v[38:39] op_sel_hi:[0,1]
	v_pk_mul_f32 v[14:15], v[56:57], v[32:33] op_sel_hi:[0,1]
	v_pk_mul_f32 v[48:49], v[56:57], v[74:75] op_sel_hi:[0,1]
	v_pk_mul_f32 v[64:65], v[56:57], v[72:73] op_sel_hi:[0,1]
	v_pk_mul_f32 v[86:87], v[56:57], v[82:83] op_sel_hi:[0,1]
	v_pk_mul_f32 v[54:55], v[22:23], v[54:55] op_sel_hi:[0,1]
	v_pk_mul_f32 v[52:53], v[22:23], v[52:53] op_sel_hi:[0,1]
	v_pk_mul_f32 v[56:57], v[22:23], v[62:63] op_sel_hi:[0,1]
	v_pk_mul_f32 v[58:59], v[22:23], v[60:61] op_sel_hi:[0,1]
	v_pk_mul_f32 v[60:61], v[22:23], v[44:45] op_sel_hi:[0,1]
	v_pk_mul_f32 v[76:77], v[22:23], v[42:43] op_sel_hi:[0,1]
	v_pk_mul_f32 v[68:69], v[22:23], v[36:37] op_sel_hi:[0,1]
	v_pk_mul_f32 v[78:79], v[22:23], v[34:35] op_sel_hi:[0,1]
	v_pk_mul_f32 v[70:71], v[22:23], v[28:29] op_sel_hi:[0,1]
	v_pk_mul_f32 v[72:73], v[22:23], v[26:27] op_sel_hi:[0,1]
	v_pk_mul_f32 v[74:75], v[22:23], v[134:135] op_sel_hi:[0,1]
	v_pk_mul_f32 v[80:81], v[22:23], v[132:133] op_sel_hi:[0,1]
	v_pk_mul_f32 v[40:41], v[22:23], v[138:139] op_sel_hi:[0,1]
	v_pk_mul_f32 v[82:83], v[22:23], v[136:137] op_sel_hi:[0,1]
	v_pk_mul_f32 v[34:35], v[22:23], v[90:91] op_sel_hi:[0,1]
	v_pk_mul_f32 v[42:43], v[22:23], v[88:89] op_sel_hi:[0,1]
	v_cmp_eq_u32_e32 vcc, 1, v127
	s_and_saveexec_b64 s[4:5], vcc
	s_cbranch_execz .LBB0_454
	v_lshlrev_b32_e32 v22, 14, v128
	v_add3_u32 v22, 0, v126, v22
	ds_write2st64_b32 v22, v6, v7 offset1:1
	ds_write2st64_b32 v22, v4, v5 offset0:2 offset1:3
	ds_write2st64_b32 v22, v52, v53 offset0:4 offset1:5
	ds_write2st64_b32 v22, v54, v55 offset0:6 offset1:7
	ds_write2st64_b32 v22, v12, v13 offset0:8 offset1:9
	ds_write2st64_b32 v22, v2, v3 offset0:10 offset1:11
	ds_write2st64_b32 v22, v58, v59 offset0:12 offset1:13
	ds_write2st64_b32 v22, v56, v57 offset0:14 offset1:15
	ds_write2st64_b32 v22, v10, v11 offset0:16 offset1:17
	ds_write2st64_b32 v22, v8, v9 offset0:18 offset1:19
	ds_write2st64_b32 v22, v76, v77 offset0:20 offset1:21
	ds_write2st64_b32 v22, v60, v61 offset0:22 offset1:23
	ds_write2st64_b32 v22, v20, v21 offset0:24 offset1:25
	ds_write2st64_b32 v22, v16, v17 offset0:26 offset1:27
	ds_write2st64_b32 v22, v78, v79 offset0:28 offset1:29
	ds_write2st64_b32 v22, v68, v69 offset0:30 offset1:31
	ds_write2st64_b32 v22, v18, v19 offset0:32 offset1:33
	ds_write2st64_b32 v22, v14, v15 offset0:34 offset1:35
	ds_write2st64_b32 v22, v72, v73 offset0:36 offset1:37
	ds_write2st64_b32 v22, v70, v71 offset0:38 offset1:39
	ds_write2st64_b32 v22, v64, v65 offset0:40 offset1:41
	ds_write2st64_b32 v22, v48, v49 offset0:42 offset1:43
	ds_write2st64_b32 v22, v80, v81 offset0:44 offset1:45
	ds_write2st64_b32 v22, v74, v75 offset0:46 offset1:47
	ds_write2st64_b32 v22, v86, v87 offset0:48 offset1:49
	ds_write2st64_b32 v22, v46, v47 offset0:50 offset1:51
	ds_write2st64_b32 v22, v82, v83 offset0:52 offset1:53
	ds_write2st64_b32 v22, v40, v41 offset0:54 offset1:55
	ds_write2st64_b32 v22, v84, v85 offset0:56 offset1:57
	ds_write2st64_b32 v22, v66, v67 offset0:58 offset1:59
	ds_write2st64_b32 v22, v42, v43 offset0:60 offset1:61
	ds_write2st64_b32 v22, v34, v35 offset0:62 offset1:63

	.amdhsa_kernel _Z14fwd_megakernel6Params
		.amdhsa_group_segment_fixed_size 0
		.amdhsa_private_segment_fixed_size 0
		.amdhsa_kernarg_size 672
		.amdhsa_user_sgpr_count 2
		.amdhsa_user_sgpr_dispatch_ptr 0
		.amdhsa_user_sgpr_queue_ptr 0
		.amdhsa_user_sgpr_kernarg_segment_ptr 1
		.amdhsa_user_sgpr_dispatch_id 0
		.amdhsa_user_sgpr_kernarg_preload_length 0
		.amdhsa_user_sgpr_kernarg_preload_offset 0
		.amdhsa_user_sgpr_private_segment_size 0
		.amdhsa_uses_dynamic_stack 0
		.amdhsa_enable_private_segment 0
		.amdhsa_system_sgpr_workgroup_id_x 1
		.amdhsa_system_sgpr_workgroup_id_y 0
		.amdhsa_system_sgpr_workgroup_id_z 0
		.amdhsa_system_sgpr_workgroup_info 0
		.amdhsa_system_vgpr_workitem_id 0
		.amdhsa_next_free_vgpr 256
		.amdhsa_next_free_sgpr 98
		.amdhsa_accum_offset 256
		.amdhsa_reserve_vcc 1
		.amdhsa_float_round_mode_32 0
		.amdhsa_float_round_mode_16_64 0
		.amdhsa_float_denorm_mode_32 3
		.amdhsa_float_denorm_mode_16_64 3
		.amdhsa_dx10_clamp 1
		.amdhsa_ieee_mode 1
		.amdhsa_fp16_overflow 0
		.amdhsa_tg_split 0
		.amdhsa_exception_fp_ieee_invalid_op 0
		.amdhsa_exception_fp_denorm_src 0
		.amdhsa_exception_fp_ieee_div_zero 0
		.amdhsa_exception_fp_ieee_overflow 0
		.amdhsa_exception_fp_ieee_underflow 0
		.amdhsa_exception_fp_ieee_inexact 0
		.amdhsa_exception_int_div_zero 0
	.end_amdhsa_kernel

amdhsa.kernels:
  - .agpr_count:     0
    .args:
      - .offset:         0
        .size:           416
        .value_kind:     by_value
      - .offset:         416
        .size:           4
        .value_kind:     hidden_block_count_x
      - .offset:         420
        .size:           4
        .value_kind:     hidden_block_count_y
      - .offset:         424
        .size:           4
        .value_kind:     hidden_block_count_z
      - .offset:         428
        .size:           2
        .value_kind:     hidden_group_size_x
      - .offset:         430
        .size:           2
        .value_kind:     hidden_group_size_y
      - .offset:         432
        .size:           2
        .value_kind:     hidden_group_size_z
      - .offset:         434
        .size:           2
        .value_kind:     hidden_remainder_x
      - .offset:         436
        .size:           2
        .value_kind:     hidden_remainder_y
      - .offset:         438
        .size:           2
        .value_kind:     hidden_remainder_z
      - .offset:         456
        .size:           8
        .value_kind:     hidden_global_offset_x
      - .offset:         464
        .size:           8
        .value_kind:     hidden_global_offset_y
      - .offset:         472
        .size:           8
        .value_kind:     hidden_global_offset_z
      - .offset:         480
        .size:           2
        .value_kind:     hidden_grid_dims
      - .offset:         536
        .size:           4
        .value_kind:     hidden_dynamic_lds_size
    .group_segment_fixed_size: 0
    .kernarg_segment_align: 8
    .kernarg_segment_size: 672
    .language:       OpenCL C
    .language_version:
      - 2
      - 0
    .max_flat_workgroup_size: 512
    .name:           _Z14fwd_megakernel6Params
    .private_segment_fixed_size: 0
    .sgpr_count:     104
    .sgpr_spill_count: 104
    .symbol:         _Z14fwd_megakernel6Params.kd
    .uniform_work_group_size: 1
    .uses_dynamic_stack: false
    .vgpr_count:     256
    .vgpr_spill_count: 0
    .wavefront_size: 64
